# E2: two-item sgu_ln blocks skip pool_d (rebalance)
# speedup vs baseline: 1.0083x; 1.0083x over previous
; DI int get_tid() { int t = threadIdx.x; asm volatile("" : "+v"(t)); return t; }
; DI int get_bid() { int b = blockIdx.x; asm volatile("" : "+s"(b)); return b; }
; DI void pool_d_items(const Params& p, int e) {
;   const u16* a = (const u16*)(p.ws + OFF_A);
;   u16* d = (u16*)(p.ws + OFF_H);
;   const float* hist = p.cache_pool + (size_t)e * 16 * 15 * 1024;
;   const int tid = get_tid(), lane = tid & 63;
;   for (int wi = get_bid() * 4 + (tid >> 6); wi < (M_TOK / 2) * 4; wi += gridDim.x * 4) {
;     const int g = __builtin_amdgcn_readfirstlane(wi & 3);
;     const int r = (wi >> 2) * 2 + (lane >> 5), ch0 = g * 256 + (lane & 31) * 8;
;     if (g == 0) pool_d_one<2>(a, d, hist, r, ch0);
.LBB0_383:
	v_mov_b32_e32 v2, v185
	s_mov_b32 s4, s2
	v_readlane_b32 s98, v255, 11
	s_mov_b32 s99, s3
	s_cmp_lg_u32 s98, 0x200
	s_cbranch_scc1 .Lpool_skip_0
	s_sub_i32 s4, s2, 64
	s_cmp_lt_i32 s4, 0
	s_cselect_b32 s4, 0x2100, s4
	s_sub_i32 s99, s3, 0x100
.Lpool_skip_0:
	s_nop 0
	v_ashrrev_i32_e32 v1, 6, v2
	v_lshl_add_u32 v1, s4, 2, v1
	s_mov_b32 s4, 0x8400
	v_cmp_gt_i32_e32 vcc, s4, v1
	s_and_saveexec_b64 s[40:41], vcc
	s_cbranch_execz .LBB0_413
	v_bfe_u32 v224, v2, 5, 1
	v_lshlrev_b32_e32 v2, 3, v2
	v_and_b32_e32 v225, 0xf8, v2
	s_mov_b64 s[42:43], 0
	s_branch .LBB0_387

; DI int get_tid() { int t = threadIdx.x; asm volatile("" : "+v"(t)); return t; }
; DI int get_bid() { int b = blockIdx.x; asm volatile("" : "+s"(b)); return b; }
; template <int W>
; DI void pool_d_one(const u16* __restrict__ a, u16* __restrict__ d, const float* __restrict__ hist, int r, int ch0) {
;     ...
;   *(u32x4*)(d + (size_t)r * 1024 + ch0) = o;
; }
; DI void pool_d_items(const Params& p, int e) {
;   const u16* a = (const u16*)(p.ws + OFF_A);
;   u16* d = (u16*)(p.ws + OFF_H);
;   const float* hist = p.cache_pool + (size_t)e * 16 * 15 * 1024;
;   const int tid = get_tid(), lane = tid & 63;
;   for (int wi = get_bid() * 4 + (tid >> 6); wi < (M_TOK / 2) * 4; wi += gridDim.x * 4) {
.LBB0_386:
	v_add_u32_e32 v1, s99, v1
	s_mov_b32 s4, 0x83ff
	v_cvt_pk_bf16_f32 v5, v6, v7
	v_lshl_add_u64 v[6:7], s[0:1], 0, v[186:187]
	v_cmp_lt_i32_e32 vcc, s4, v1
	v_lshl_add_u64 v[6:7], v[182:183], 1, v[6:7]
	s_or_b64 s[42:43], vcc, s[42:43]
	global_store_dwordx4 v[6:7], v[2:5], off
	s_andn2_b64 exec, exec, s[42:43]
	s_cbranch_execz .LBB0_413

; DI int get_tid() { int t = threadIdx.x; asm volatile("" : "+v"(t)); return t; }
; DI int get_bid() { int b = blockIdx.x; asm volatile("" : "+s"(b)); return b; }
; DI void pool_d_items(const Params& p, int e) {
;   const u16* a = (const u16*)(p.ws + OFF_A);
;   u16* d = (u16*)(p.ws + OFF_H);
;   const float* hist = p.cache_pool + (size_t)e * 16 * 15 * 1024;
;   const int tid = get_tid(), lane = tid & 63;
;   for (int wi = get_bid() * 4 + (tid >> 6); wi < (M_TOK / 2) * 4; wi += gridDim.x * 4) {
;     const int g = __builtin_amdgcn_readfirstlane(wi & 3);
;     const int r = (wi >> 2) * 2 + (lane >> 5), ch0 = g * 256 + (lane & 31) * 8;
;     if (g == 0) pool_d_one<2>(a, d, hist, r, ch0);
.LBB0_1231:
	v_mov_b32_e32 v0, v185
	s_mov_b32 s4, s2
	v_readlane_b32 s98, v255, 11
	s_mov_b32 s99, s3
	s_cmp_lg_u32 s98, 0x200
	s_cbranch_scc1 .Lpool_skip_1
	s_sub_i32 s4, s2, 64
	s_cmp_lt_i32 s4, 0
	s_cselect_b32 s4, 0x2100, s4
	s_sub_i32 s99, s3, 0x100
.Lpool_skip_1:
	s_nop 0
	v_ashrrev_i32_e32 v1, 6, v0
	v_lshl_add_u32 v196, s4, 2, v1
	s_mov_b32 s4, 0x8400
	v_cmp_gt_i32_e32 vcc, s4, v196
	s_and_saveexec_b64 s[40:41], vcc
	s_cbranch_execz .LBB0_1261
	v_bfe_u32 v197, v0, 5, 1
	v_lshlrev_b32_e32 v0, 3, v0
	v_and_b32_e32 v224, 0xf8, v0
	s_mov_b64 s[42:43], 0
	s_branch .LBB0_1235

; DI int get_tid() { int t = threadIdx.x; asm volatile("" : "+v"(t)); return t; }
; DI int get_bid() { int b = blockIdx.x; asm volatile("" : "+s"(b)); return b; }
; template <int W>
; DI void pool_d_one(const u16* __restrict__ a, u16* __restrict__ d, const float* __restrict__ hist, int r, int ch0) {
;     ...
;   *(u32x4*)(d + (size_t)r * 1024 + ch0) = o;
; }
; DI void pool_d_items(const Params& p, int e) {
;   const u16* a = (const u16*)(p.ws + OFF_A);
;   u16* d = (u16*)(p.ws + OFF_H);
;   const float* hist = p.cache_pool + (size_t)e * 16 * 15 * 1024;
;   const int tid = get_tid(), lane = tid & 63;
;   for (int wi = get_bid() * 4 + (tid >> 6); wi < (M_TOK / 2) * 4; wi += gridDim.x * 4) {
.LBB0_1234:
	v_add_u32_e32 v196, s99, v196
	s_mov_b32 s4, 0x83ff
	v_cvt_pk_bf16_f32 v3, v4, v5
	v_lshl_add_u64 v[4:5], s[0:1], 0, v[180:181]
	v_cmp_lt_i32_e32 vcc, s4, v196
	v_lshl_add_u64 v[4:5], v[182:183], 1, v[4:5]
	s_or_b64 s[42:43], vcc, s[42:43]
	global_store_dwordx4 v[4:5], v[0:3], off
	s_andn2_b64 exec, exec, s[42:43]
	s_cbranch_execz .LBB0_1261
